# combined: v53 + out-proj next-tile prefetch + MLA one barrier per two tiles + MLA-up counted vmcnt / hoisted LDS addresses + no early vmcnt(0) in MLA/DIFF item prologues
# speedup vs baseline: 1.0061x; 1.0061x over previous
; DI float bf2f(u16 b) { return __uint_as_float(((unsigned)b) << 16); }
; DI int crow(int r, int hh) { return (r & 3) + 8 * (r >> 2) + 4 * hh; }
; DI void phase_mla_up(const Params& p, int layer, char* lds) {
;     ...
;       const int K = part == 0 ? 192 : 128, acol = part == 0 ? C_CQ : C_CKV, STR = (K + 8) * 2, CPR = K / 8;
;       const int NCT = part == 0 ? 9 : 12;
;       const u16* Wt = part == 0 ? wuq : wukv;
;       __syncthreads();
;       for (int c = tid; c < 128 * CPR; c += NTHR) { int row = c / CPR, ch = c % CPR;
;         *(u32x4*)(As + row * STR + ch * 16) = *(const u32x4*)(H + (size_t)(m0 + row) * DIN + acol + ch * 8); }
;       __syncthreads();
;       {
;         int row = tid >> 2, part4 = tid & 3, n = K / 4; float ss = 0.f;
;         const u16* ar = (const u16*)(As + row * STR) + part4 * n;
;         for (int i = 0; i < n; ++i) { float v = bf2f(ar[i]); ss += v * v; }
;         ss += __shfl_xor(ss, 1); ss += __shfl_xor(ss, 2);
;         if (part4 == 0) rinv[row] = rsqrtf(ss / (float)K + 1e-6f);
;       }
;       const int NCT2 = (NCT + 1) / 2, NOUT = NCT * 64;
;       u32x4 rw[6];
;       auto wload = [&](int ct) {
;         int tl = tid; asm volatile("" : "+v"(tl));
; #pragma unroll
;         for (int i = 0; i < 6; ++i) { const int c = tl + NTHR * i; if (c < 128 * CPR) rw[i] = *(const u32x4*)(Wt + (size_t)ct * 128 * K + c * 8); }
;       };
;       __syncthreads();
;       float rv[16];
; #pragma unroll
;       for (int r = 0; r < 16; ++r) rv[r] = rinv[32 * wm + crow(r, hh)] * (part == 0 ? QSC : 1.f);
;       const int rowb = m0 + 32 * wm + 4 * hh;
;     ...
;           int tl = tid; asm volatile("" : "+v"(tl));
; #pragma unroll
;           for (int i = 0; i < 6; ++i) { const int c = tl + NTHR * i, row = c / CPR, ch = c % CPR; if (c < 128 * CPR) *(u32x4*)(Bs + row * STR + ch * 16) = rw[i]; }
.LBB0_188:
	s_or_b64 exec, exec, s[26:27]
	v_cndmask_b32_e64 v4, 1.0, v217, s[12:13]
	s_waitcnt lgkmcnt(3)
	v_mul_f32_e32 v95, v4, v18
	v_mul_f32_e32 v96, v4, v19
	v_mul_f32_e32 v97, v4, v20
	v_mul_f32_e32 v98, v4, v21
	s_waitcnt lgkmcnt(2)
	v_mul_f32_e32 v99, v4, v14
	v_mul_f32_e32 v100, v4, v15
	v_mul_f32_e32 v101, v4, v16
	v_mul_f32_e32 v102, v4, v17
	s_waitcnt lgkmcnt(1)
	v_mul_f32_e32 v103, v4, v10
	v_mul_f32_e32 v104, v4, v11
	v_mul_f32_e32 v105, v4, v12
	v_mul_f32_e32 v106, v4, v13
	s_waitcnt lgkmcnt(0)
	v_mul_f32_e32 v107, v4, v6
	v_mul_f32_e32 v108, v4, v7
	v_mul_f32_e32 v109, v4, v8
	v_mul_f32_e32 v110, v4, v9
	v_mul_f32_e32 v4, 0x4f7ffffe, v22
	v_cvt_u32_f32_e32 v4, v4
	s_and_b64 s[26:27], s[12:13], exec
	s_cselect_b32 s26, 9, 12
	s_add_i32 s27, s26, 1
	s_sub_i32 s12, 0, s29
	s_lshr_b32 s77, s27, 1
	s_lshl_b32 s73, s26, 6
	v_mul_lo_u32 v6, s12, v4
	s_lshl_b32 s49, s49, 8
	v_mul_hi_u32 v6, v4, v6
	s_add_u32 s24, s24, s49
	s_mov_b32 s53, 0
	v_add_u32_e32 v111, v4, v6
	s_addc_u32 s25, s25, 0
	v_mov_b32_e32 v78, v89
	s_waitcnt vmcnt(0)
	v_mov_b32_e32 v4, v59
	v_sub_u32_e32 v7, 0, v4
	v_max_i32_e32 v7, v4, v7
	v_mul_hi_u32 v8, v7, v111
	v_mul_lo_u32 v9, v8, s29
	v_sub_u32_e32 v7, v7, v9
	v_add_u32_e32 v9, 1, v8
	v_cmp_le_u32_e32 vcc, s29, v7
	v_ashrrev_i32_e32 v6, 31, v4
	s_nop 0
	v_cndmask_b32_e32 v8, v8, v9, vcc
	v_subrev_u32_e32 v9, s29, v7
	v_cndmask_b32_e32 v7, v7, v9, vcc
	v_add_u32_e32 v9, 1, v8
	v_cmp_le_u32_e32 vcc, s29, v7
	s_nop 1
	v_cndmask_b32_e32 v7, v8, v9, vcc
	v_xor_b32_e32 v7, v7, v6
	v_sub_u32_e32 v6, v7, v6
	v_mul_lo_u32 v7, v6, s29
	v_sub_u32_e32 v7, v4, v7
	v_mul_lo_u32 v6, v6, s76
	v_lshlrev_b32_e32 v7, 4, v7
	v_add3_u32 v6, 0, v6, v7
	v_mov_b32_e32 v148, v6
	v_add_u32_e32 v6, 0x200, v4
	v_sub_u32_e32 v8, 0, v6
	v_max_i32_e32 v8, v6, v8
	v_mul_hi_u32 v9, v8, v111
	v_mul_lo_u32 v10, v9, s29
	v_sub_u32_e32 v8, v8, v10
	v_add_u32_e32 v10, 1, v9
	v_cmp_le_u32_e32 vcc, s29, v8
	v_ashrrev_i32_e32 v7, 31, v6
	s_nop 0
	v_cndmask_b32_e32 v9, v9, v10, vcc
	v_subrev_u32_e32 v10, s29, v8
	v_cndmask_b32_e32 v8, v8, v10, vcc
	v_add_u32_e32 v10, 1, v9
	v_cmp_le_u32_e32 vcc, s29, v8
	s_nop 1
	v_cndmask_b32_e32 v8, v9, v10, vcc
	v_xor_b32_e32 v8, v8, v7
	v_sub_u32_e32 v7, v8, v7
	v_mul_lo_u32 v8, v7, s29
	v_sub_u32_e32 v6, v6, v8
	v_mul_lo_u32 v7, v7, s76
	v_lshlrev_b32_e32 v6, 4, v6
	v_add3_u32 v6, 0, v7, v6
	v_mov_b32_e32 v191, v6
	v_add_u32_e32 v6, 0x400, v4
	v_sub_u32_e32 v8, 0, v6
	v_max_i32_e32 v8, v6, v8
	v_mul_hi_u32 v9, v8, v111
	v_mul_lo_u32 v10, v9, s29
	v_sub_u32_e32 v8, v8, v10
	v_add_u32_e32 v10, 1, v9
	v_cmp_le_u32_e32 vcc, s29, v8
	v_ashrrev_i32_e32 v7, 31, v6
	s_nop 0
	v_cndmask_b32_e32 v9, v9, v10, vcc
	v_subrev_u32_e32 v10, s29, v8
	v_cndmask_b32_e32 v8, v8, v10, vcc
	v_add_u32_e32 v10, 1, v9
	v_cmp_le_u32_e32 vcc, s29, v8
	s_nop 1
	v_cndmask_b32_e32 v8, v9, v10, vcc
	v_xor_b32_e32 v8, v8, v7
	v_sub_u32_e32 v7, v8, v7
	v_mul_lo_u32 v8, v7, s29
	v_sub_u32_e32 v6, v6, v8
	v_mul_lo_u32 v7, v7, s76
	v_lshlrev_b32_e32 v6, 4, v6
	v_add3_u32 v6, 0, v7, v6
	v_mov_b32_e32 v200, v6
	v_add_u32_e32 v6, 0x600, v4
	v_sub_u32_e32 v8, 0, v6
	v_max_i32_e32 v8, v6, v8
	v_mul_hi_u32 v9, v8, v111
	v_mul_lo_u32 v10, v9, s29
	v_sub_u32_e32 v8, v8, v10
	v_add_u32_e32 v10, 1, v9
	v_cmp_le_u32_e32 vcc, s29, v8
	v_ashrrev_i32_e32 v7, 31, v6
	s_nop 0
	v_cndmask_b32_e32 v9, v9, v10, vcc
	v_subrev_u32_e32 v10, s29, v8
	v_cndmask_b32_e32 v8, v8, v10, vcc
	v_add_u32_e32 v10, 1, v9
	v_cmp_le_u32_e32 vcc, s29, v8
	s_nop 1
	v_cndmask_b32_e32 v8, v9, v10, vcc
	v_xor_b32_e32 v8, v8, v7
	v_sub_u32_e32 v7, v8, v7
	v_mul_lo_u32 v8, v7, s29
	v_sub_u32_e32 v6, v6, v8
	v_mul_lo_u32 v7, v7, s76
	v_lshlrev_b32_e32 v6, 4, v6
	v_add3_u32 v6, 0, v7, v6
	v_mov_b32_e32 v201, v6
	v_add_u32_e32 v6, 0x800, v4
	v_sub_u32_e32 v8, 0, v6
	v_max_i32_e32 v8, v6, v8
	v_mul_hi_u32 v9, v8, v111
	v_mul_lo_u32 v10, v9, s29
	v_sub_u32_e32 v8, v8, v10
	v_add_u32_e32 v10, 1, v9
	v_cmp_le_u32_e32 vcc, s29, v8
	v_ashrrev_i32_e32 v7, 31, v6
	s_nop 0
	v_cndmask_b32_e32 v9, v9, v10, vcc
	v_subrev_u32_e32 v10, s29, v8
	v_cndmask_b32_e32 v8, v8, v10, vcc
	v_add_u32_e32 v10, 1, v9
	v_cmp_le_u32_e32 vcc, s29, v8
	s_nop 1
	v_cndmask_b32_e32 v8, v9, v10, vcc
	v_xor_b32_e32 v8, v8, v7
	v_sub_u32_e32 v7, v8, v7
	v_mul_lo_u32 v8, v7, s29
	v_sub_u32_e32 v6, v6, v8
	v_mul_lo_u32 v7, v7, s76
	v_lshlrev_b32_e32 v6, 4, v6
	v_add3_u32 v6, 0, v7, v6
	v_mov_b32_e32 v208, v6
	v_add_u32_e32 v4, 0xa00, v4
	v_sub_u32_e32 v7, 0, v4
	v_max_i32_e32 v7, v4, v7
	v_mul_hi_u32 v8, v7, v111
	v_mul_lo_u32 v9, v8, s29
	v_sub_u32_e32 v7, v7, v9
	v_add_u32_e32 v9, 1, v8
	v_cmp_le_u32_e32 vcc, s29, v7
	v_ashrrev_i32_e32 v6, 31, v4
	s_nop 0
	v_cndmask_b32_e32 v8, v8, v9, vcc
	v_subrev_u32_e32 v9, s29, v7
	v_cndmask_b32_e32 v7, v7, v9, vcc
	v_add_u32_e32 v9, 1, v8
	v_cmp_le_u32_e32 vcc, s29, v7
	s_nop 1
	v_cndmask_b32_e32 v7, v8, v9, vcc
	v_xor_b32_e32 v7, v7, v6
	v_sub_u32_e32 v6, v7, v6
	v_mul_lo_u32 v7, v6, s29
	v_sub_u32_e32 v4, v4, v7
	v_mul_lo_u32 v6, v6, s76
	v_lshlrev_b32_e32 v4, 4, v4
	v_add3_u32 v4, 0, v6, v4
	v_mov_b32_e32 v209, v4
	s_branch .LBB0_191

; #define LDS_BARRIER() asm volatile("s_waitcnt lgkmcnt(0)\n\ts_barrier" ::: "memory")
; DI void phase_mla_up(const Params& p, int layer, char* lds) {
;     ...
;         {
;           int tl = tid; asm volatile("" : "+v"(tl));
; #pragma unroll
;           for (int i = 0; i < 6; ++i) { const int c = tl + NTHR * i, row = c / CPR, ch = c % CPR; if (c < 128 * CPR) *(u32x4*)(Bs + row * STR + ch * 16) = rw[i]; }
;         }
;         LDS_BARRIER();
.LBB0_191:
	v_mov_b32_e32 v4, v59
	s_nop 0
	v_cmp_gt_i32_e32 vcc, s93, v4
	s_and_saveexec_b64 s[12:13], vcc
	s_cbranch_execz .LBB0_193
	s_waitcnt vmcnt(32)
	ds_write_b128 v148, v[0:3] offset:51200
.LBB0_193:
	s_or_b64 exec, exec, s[12:13]
	v_add_u32_e32 v6, 0x200, v4
	v_cmp_gt_i32_e32 vcc, s93, v6
	s_and_saveexec_b64 s[12:13], vcc
	s_cbranch_execz .LBB0_195
	s_waitcnt vmcnt(32)
	ds_write_b128 v191, v[38:41] offset:51200
.LBB0_195:
	s_or_b64 exec, exec, s[12:13]
	v_add_u32_e32 v6, 0x400, v4
	v_cmp_gt_i32_e32 vcc, s93, v6
	s_and_saveexec_b64 s[12:13], vcc
	s_cbranch_execz .LBB0_197
	s_waitcnt vmcnt(32)
	ds_write_b128 v200, v[42:45] offset:51200
.LBB0_197:
	s_or_b64 exec, exec, s[12:13]
	v_add_u32_e32 v6, 0x600, v4
	v_cmp_gt_i32_e32 vcc, s93, v6
	s_and_saveexec_b64 s[12:13], vcc
	s_cbranch_execz .LBB0_199
	s_waitcnt vmcnt(32)
	ds_write_b128 v201, v[46:49] offset:51200
.LBB0_199:
	s_or_b64 exec, exec, s[12:13]
	v_add_u32_e32 v6, 0x800, v4
	v_cmp_gt_i32_e32 vcc, s93, v6
	s_and_saveexec_b64 s[12:13], vcc
	s_cbranch_execz .LBB0_201
	s_waitcnt vmcnt(32)
	ds_write_b128 v208, v[50:53] offset:51200
.LBB0_201:
	s_or_b64 exec, exec, s[12:13]
	v_add_u32_e32 v4, 0xa00, v4
	v_cmp_gt_i32_e32 vcc, s93, v4
	s_and_saveexec_b64 s[12:13], vcc
	s_cbranch_execz .LBB0_203
	s_waitcnt vmcnt(32)
	ds_write_b128 v209, v[54:57] offset:51200

; template <int MODE>
; DI void attn_item(const Params& p, int layer, int bh, int qb, char* lds) {
;     ...
;   bf16x8 qf[NMAP][QS];
;   {
;     const u16* qrow = Qg + (size_t)(q0w + l32) * qstr + hh * 8;
; #pragma unroll
;     for (int mp = 0; mp < NMAP; ++mp)
; #pragma unroll
;       for (int st = 0; st < QS; ++st) qf[mp][st] = *(const bf16x8*)(qrow + (mp * QS + st) * 16);
;   }
;   f32x16 O[NMAP][2]; float m = 0.f, l[NMAP];
; #pragma unroll
;   for (int mp = 0; mp < NMAP; ++mp) {
; #pragma unroll
;     for (int r = 0; r < 16; ++r) { O[mp][0][r] = 0.f; O[mp][1][r] = 0.f; }
;     l[mp] = 0.f;
;   }
;   if (MODE == 2) { m = p.sink[layer * 6 + hd] * LOG2E; l[0] = (hh == 0) ? 1.f : 0.f; }
;   int kt0 = 0, kt1 = S / 64;
;   if (MODE == 2) { kt0 = (q0 - 128) / 64; if (kt0 < 0) kt0 = 0; kt1 = (q0 + 384) / 64; if (kt1 > S / 64) kt1 = S / 64; }
;   const int nt = kt1 - kt0;
;   constexpr int KSTRG = MODE == 0 ? 96 : 64, VSTRG = 64;
;   u32x4 rkA[KCH], rvA[1], rkB[KCH], rvB[1];
;   const __amdgpu_buffer_rsrc_t krsrc = __builtin_amdgcn_make_buffer_rsrc((void*)Kg, 0, S * KSTRG * 2, 0x00027000);
;   const __amdgpu_buffer_rsrc_t vrsrc = __builtin_amdgcn_make_buffer_rsrc((void*)Vg, 0, S * VSTRG * 2, 0x00027000);
;   auto gload = [&](int kt, u32x4 (&rk)[KCH], u32x4 (&rv)[1]) {
;     const int ksoff = kt * (64 * KSTRG * 2), vsoff = kt * (64 * VSTRG * 2);
; #pragma unroll
;     for (int i = 0; i < KCH; ++i) if (tid + NTHR * i < KCHUNKS) rk[i] = __builtin_amdgcn_raw_buffer_load_b128(krsrc, tid * 16 + NTHR * 16 * i, ksoff, 0);
;     rv[0] = __builtin_amdgcn_raw_buffer_load_b128(vrsrc, tid * 16, vsoff, 0);
;   };
;   auto lstore = [&](int st, const u32x4 (&rk)[KCH], const u32x4 (&rv)[1]) {
;     char* Ks = stage0 + st * STAGE;
; #pragma unroll
;     for (int i = 0; i < KCH; ++i) { int c = tid + NTHR * i, row = c / KCPR, ch = c % KCPR; if (c < KCHUNKS) *(u32x4*)(Ks + row * KSTR + ch * 16) = rk[i]; }
;     { int row = tid >> 3, ch = tid & 7; *(u32x4*)(Ks + KBYTES + row * VSTR + ch * 16) = rv[0]; }
;   };
;   const unsigned vlane = (unsigned)((4 * hh + ((lane & 15) >> 2)) * VSTR + 32 * ((lane >> 4) & 1) + 8 * (lane & 3));
;   bf16x8 kaug, qaug;
;   { u32x4 tk = {hh == 0 ? 0x3F803F80u : 0u, 0u, 0u, 0u}; kaug = __builtin_bit_cast(bf16x8, tk); qaug = __builtin_bit_cast(bf16x8, (u32x4){0u, 0u, 0u, 0u}); }
;     ...
;   __syncthreads();
;   gload(kt0, rkA, rvA); lstore(0, rkA, rvA);
.LBB0_403:
	s_ashr_i32 s5, s60, 5
	s_and_b32 s4, s60, 7
	s_and_b32 s5, s5, -8
	v_mov_b32_e32 v14, v184
	s_or_b32 s4, s5, s4
	s_lshl_b32 s5, s60, 5
	v_ashrrev_i32_e32 v0, 1, v14
	s_and_b32 s5, s5, 0x1f00
	v_and_b32_e32 v0, 0xffffffe0, v0
	v_add_u32_e32 v186, s5, v0
	s_mul_hi_i32 s5, s4, 0x2aaaaaab
	s_lshr_b32 s6, s5, 31
	s_add_i32 s10, s5, s6
	s_mul_i32 s5, s10, 6
	s_sub_i32 s52, s4, s5
	s_mul_i32 s6, s10, 0x900000
	v_readlane_b32 s8, v254, 45
	s_mul_hi_i32 s5, s10, 0x900000
	v_readlane_b32 s9, v254, 46
	s_add_u32 s8, s8, s6
	s_mul_i32 s6, s52, 0x60
	s_addc_u32 s5, s9, s5
	s_ashr_i32 s7, s6, 31
	s_lshl_b64 s[6:7], s[6:7], 1
	s_add_u32 s6, s8, s6
	v_and_b32_e32 v204, 31, v14
	s_addc_u32 s7, s5, s7
	v_bfe_u32 v15, v14, 5, 1
	v_or_b32_e32 v2, v186, v204
	v_mov_b64_e32 v[0:1], s[6:7]
	s_movk_i32 s5, 0x480
	v_mad_i64_i32 v[0:1], s[6:7], v2, s5, v[0:1]
	v_lshlrev_b32_e32 v16, 4, v15
	v_mov_b32_e32 v17, v5
	v_lshl_add_u64 v[0:1], v[0:1], 0, v[16:17]
	global_load_dwordx4 v[104:107], v[0:1], off
	global_load_dwordx4 v[108:111], v[0:1], off offset:32
	global_load_dwordx4 v[112:115], v[0:1], off offset:64
	global_load_dwordx4 v[116:119], v[0:1], off offset:96
	global_load_dwordx4 v[120:123], v[0:1], off offset:128
	global_load_dwordx4 v[124:127], v[0:1], off offset:160
	s_ashr_i32 s5, s4, 31
	s_mul_hi_i32 s6, s4, 0x180000
	s_mul_i32 s7, s4, 0x180000
	s_lshl_b64 s[4:5], s[4:5], 20
	s_add_u32 s12, s68, s4
	s_addc_u32 s11, s69, s5
	s_add_u32 s20, s66, s7
	s_addc_u32 s4, s67, s6
	s_and_b32 s21, s4, 0xffff
	s_movk_i32 s4, 0x300
	v_cmp_gt_i32_e64 s[4:5], s4, v14
	v_lshlrev_b32_e32 v187, 4, v14
	v_mov_b32_e32 v100, 0
	v_mov_b32_e32 v96, 0
	v_mov_b32_e32 v97, 0
	v_mov_b32_e32 v98, 0
	v_mov_b32_e32 v99, 0
	s_barrier
	s_and_b32 s13, s11, 0xffff
	s_ashr_i32 s11, s10, 31
	s_mov_b32 s23, s15
	v_bfe_u32 v206, v184, 5, 1
	v_lshlrev_b32_e32 v206, 2, v206
	v_and_b32_e32 v196, 31, v184
	v_bfe_u32 v197, v184, 5, 1
	v_mov_b32_e32 v199, 208
	v_mul_u32_u24_e32 v200, v196, v199
	v_lshl_add_u32 v200, v197, 4, v200
	v_bfe_u32 v199, v184, 2, 2
	v_lshl_add_u32 v199, v197, 2, v199
	v_mov_b32_e32 v208, 192
	v_mul_u32_u24_e32 v201, v199, v208
	v_bfe_u32 v199, v184, 4, 1
	v_lshl_add_u32 v201, v199, 5, v201
	v_and_b32_e32 v199, 3, v184
	v_lshl_add_u32 v201, v199, 3, v201
	v_mov_b32_e32 v208, 0xaaab
	v_mul_u32_u24_e32 v196, v184, v208
	v_lshrrev_b32_e32 v196, 19, v196
	v_mul_u32_u24_e32 v197, 12, v196
	v_sub_u32_e32 v197, v184, v197
	v_mov_b32_e32 v199, 208
	v_mul_u32_u24_e32 v202, v196, v199
	v_lshl_add_u32 v202, v197, 4, v202
	v_lshrrev_b32_e32 v196, 1, v184
	v_add_u32_e32 v196, 0x200, v196
	v_mul_u32_u24_e32 v197, v196, v208
	v_lshrrev_b32_e32 v197, 19, v197
	v_mul_u32_u24_e32 v209, 12, v197
	v_sub_u32_e32 v196, v196, v209
	v_mul_u32_u24_e32 v203, v197, v199
	v_lshl_add_u32 v203, v196, 4, v203
	v_and_b32_e32 v196, 1, v184
	v_lshl_add_u32 v203, v196, 3, v203
	v_lshrrev_b32_e32 v196, 3, v184
	v_mov_b32_e32 v199, 192
	v_mul_u32_u24_e32 v207, v196, v199
	v_and_b32_e32 v196, 7, v184
	v_lshl_add_u32 v207, v196, 4, v207
	v_add_u32_e32 v248, 51200, v200
	v_add_u32_e32 v249, 51200, v201
	v_add_u32_e32 v250, 51200, v202
	v_add_u32_e32 v251, 51200, v203
	v_add_u32_e32 v194, 51200, v207
	v_lshlrev_b32_e32 v187, 4, v184
	v_lshlrev_b32_e32 v205, 3, v184
	v_add_u32_e32 v205, 0x2000, v205
	v_bfe_u32 v197, v184, 5, 1
	v_cmp_eq_u32_e64 s[8:9], 0, v197
	v_mov_b32_e32 v196, 0x3f803f80
	s_nop 0
	v_cndmask_b32_e64 v240, 0, v196, s[8:9]
	v_mov_b32_e32 v241, 0
	v_mov_b32_e32 v245, 0
	v_mov_b32_e32 v242, 0
	v_mov_b32_e32 v246, 0
	v_mov_b32_e32 v243, 0
	v_mov_b32_e32 v247, 0
	buffer_load_dwordx4 v[64:67], v187, s[20:23], 0 offen
	buffer_load_dwordx2 v[68:69], v205, s[20:23], 0 offen
	buffer_load_dwordx4 v[72:75], v187, s[12:15], 0 offen
	s_mov_b32 s62, 0x3000
	buffer_load_dwordx4 v[76:79], v187, s[20:23], s62 offen
	buffer_load_dwordx2 v[80:81], v205, s[20:23], s62 offen
	s_mov_b32 s62, 0x6000
	buffer_load_dwordx4 v[82:85], v187, s[20:23], s62 offen
	buffer_load_dwordx2 v[86:87], v205, s[20:23], s62 offen
	s_mov_b32 s29, 0x2000
	buffer_load_dwordx4 v[88:91], v187, s[12:15], s29 offen
	s_waitcnt vmcnt(0)
	ds_write_b128 v202, v[64:67] offset:2048
	ds_write_b64 v203, v[68:69] offset:2048
	ds_write_b128 v202, v[76:79] offset:27648
	ds_write_b64 v203, v[80:81] offset:27648
	ds_write_b128 v250, v[82:85] offset:2048
	ds_write_b64 v251, v[86:87] offset:2048
	ds_write_b128 v207, v[72:75] offset:15360
	ds_write_b128 v207, v[88:91] offset:40960
	s_mov_b32 s62, 0x9000
	buffer_load_dwordx4 v[96:99], v187, s[20:23], s62 offen
	buffer_load_dwordx2 v[100:101], v205, s[20:23], s62 offen
	s_mov_b32 s29, 0x4000
	buffer_load_dwordx4 v[188:191], v187, s[12:15], s29 offen
	s_mov_b32 s62, 0xc000
	buffer_load_dwordx4 v[230:233], v187, s[20:23], s62 offen
	buffer_load_dwordx2 v[234:235], v205, s[20:23], s62 offen
	s_mov_b32 s29, 0x6000
	buffer_load_dwordx4 v[236:239], v187, s[12:15], s29 offen
	s_mov_b32 s62, 0xf000
	s_mov_b32 s29, 0x8000
	s_waitcnt lgkmcnt(0)
	s_barrier
; template <int MODE>
; DI void attn_item(const Params& p, int layer, int bh, int qb, char* lds) {
;     ...
;         f32x16 s[2];
;         const f32x16 zero16 = {0.f, 0.f, 0.f, 0.f, 0.f, 0.f, 0.f, 0.f, 0.f, 0.f, 0.f, 0.f, 0.f, 0.f, 0.f, 0.f};
;         __builtin_amdgcn_s_setprio(1);
;         f32x16 c0tile;
;         c0tile = c0p;
; #pragma unroll
;         for (int sub = 0; sub < 2; ++sub) {
; #pragma unroll
;           for (int st = 0; st < QS; ++st) {
;             bf16x8 kf = *(const bf16x8*)(Ks + (32 * sub + l32) * KSTR + ((mp * QS + st) * 16 + hh * 8) * 2);
;             if (st == 0) s[sub] = MFMA(kf, qf[mp][st], c0tile); else s[sub] = MFMA(kf, qf[mp][st], s[sub]);
;           }
;         }
;         __builtin_amdgcn_iglp_opt(1);
;         __builtin_amdgcn_s_setprio(0);
;         if (NMAP == 1) {
;           lds_s16x4* vb = (lds_s16x4*)(Ks + KBYTES + vlane);
; #pragma unroll
;           for (int i = 0; i < 16; ++i) {
;             const int sub_ = i >> 3, ks_ = (i >> 2) & 1, dt_ = (i >> 1) & 1, g_ = i & 1;
;             vpre[i] = __builtin_amdgcn_ds_read_tr16_b64_v4i16(vb + ((32 * sub_ + 16 * ks_ + 8 * g_) * VSTR + 64 * dt_) / 8);
;           }
;           __builtin_amdgcn_sched_barrier(0);
;         }
;         if (MODE != 0 && !far) {
; #pragma unroll
;           for (int sub = 0; sub < 2; ++sub)
; #pragma unroll
;             for (int r = 0; r < 16; ++r) s[sub][r] += brow[32 * sub + (r & 3) + 8 * (r >> 2)];
;         }
;         const bool first = (MODE != 2) && (t == 0) && (mp == 0);
;         auto rebase = [&]() {
;           float mx = fmaxf(fmaxf(s[0][0], s[0][1]), s[0][2]);
; #pragma unroll
;           for (int r = 3; r < 15; r += 2) mx = fmaxf(fmaxf(mx, s[0][r]), s[0][r + 1]);
;           mx = fmaxf(mx, s[0][15]);
; #pragma unroll
;           for (int r = 0; r < 16; r += 2) mx = fmaxf(fmaxf(mx, s[1][r]), s[1][r + 1]);
;           const float rm = xchg_max(mx);
;           float delta = first ? rm : fmaxf(rm, 0.f);
;           if (delta < -1e29f) delta = 0.f;
;           m += delta;
;           const float alpha = __builtin_amdgcn_exp2f(-delta);
; #pragma unroll
;           for (int mq = 0; mq < NMAP; ++mq) {
;             l[mq] *= alpha;
; #pragma unroll
;             for (int r = 0; r < 16; ++r) { O[mq][0][r] *= alpha; O[mq][1][r] *= alpha; }
;           }
; #pragma unroll
	ds_read_b128 v[176:179], v200 offset:2048
	ds_read_b128 v[180:183], v200 offset:2080
	ds_read_b128 v[222:225], v200 offset:2112
	s_waitcnt lgkmcnt(2)
	v_mfma_f32_32x32x16_bf16 v[64:79], v[176:179], v[104:107], 0
	ds_read_b128 v[226:229], v200 offset:2144
	s_waitcnt lgkmcnt(2)
	v_mfma_f32_32x32x16_bf16 v[64:79], v[180:183], v[108:111], v[64:79]
	ds_read_b128 v[176:179], v200 offset:2176
	s_waitcnt lgkmcnt(2)
	v_mfma_f32_32x32x16_bf16 v[64:79], v[222:225], v[112:115], v[64:79]
	ds_read_b128 v[180:183], v200 offset:2208
	s_waitcnt lgkmcnt(2)
	v_mfma_f32_32x32x16_bf16 v[64:79], v[226:229], v[116:119], v[64:79]
	ds_read_b128 v[222:225], v200 offset:8704
	s_waitcnt lgkmcnt(2)
	v_mfma_f32_32x32x16_bf16 v[64:79], v[176:179], v[120:123], v[64:79]
	ds_read_b128 v[226:229], v200 offset:8736
	s_waitcnt lgkmcnt(2)
	v_mfma_f32_32x32x16_bf16 v[64:79], v[180:183], v[124:127], v[64:79]
	ds_read_b128 v[176:179], v200 offset:8768
	s_waitcnt lgkmcnt(2)
	v_mfma_f32_32x32x16_bf16 v[80:95], v[222:225], v[104:107], 0
	ds_read_b128 v[180:183], v200 offset:8800
	s_waitcnt lgkmcnt(2)
	v_mfma_f32_32x32x16_bf16 v[80:95], v[226:229], v[108:111], v[80:95]
	ds_read_b128 v[222:225], v200 offset:8832
	s_waitcnt lgkmcnt(2)
	v_mfma_f32_32x32x16_bf16 v[80:95], v[176:179], v[112:115], v[80:95]
	ds_read_b128 v[226:229], v200 offset:8864
	s_waitcnt lgkmcnt(2)
	v_mfma_f32_32x32x16_bf16 v[80:95], v[180:183], v[116:119], v[80:95]
	s_waitcnt lgkmcnt(1)
	v_mfma_f32_32x32x16_bf16 v[80:95], v[222:225], v[120:123], v[80:95]
	s_waitcnt lgkmcnt(0)
	v_mfma_f32_32x32x16_bf16 v[80:95], v[226:229], v[124:127], v[80:95]
	v_mov_b32_e32 v16, 0
	v_mov_b32_e32 v32, 0
	v_mov_b32_e32 v17, 0
	v_mov_b32_e32 v33, 0
	v_mov_b32_e32 v18, 0
	v_mov_b32_e32 v34, 0
	v_mov_b32_e32 v19, 0
	v_mov_b32_e32 v35, 0
	v_mov_b32_e32 v20, 0
	v_mov_b32_e32 v36, 0
	v_mov_b32_e32 v21, 0
	v_mov_b32_e32 v37, 0
	v_mov_b32_e32 v22, 0
	v_mov_b32_e32 v38, 0
	v_mov_b32_e32 v23, 0
	v_mov_b32_e32 v39, 0
	v_mov_b32_e32 v24, 0
	v_mov_b32_e32 v40, 0
	v_mov_b32_e32 v25, 0
	v_mov_b32_e32 v41, 0
	v_mov_b32_e32 v26, 0
	v_mov_b32_e32 v42, 0
	v_mov_b32_e32 v27, 0
	v_mov_b32_e32 v43, 0
	v_mov_b32_e32 v28, 0
	v_mov_b32_e32 v44, 0
	v_mov_b32_e32 v29, 0
	v_mov_b32_e32 v45, 0
	v_mov_b32_e32 v30, 0
	v_mov_b32_e32 v46, 0
	v_mov_b32_e32 v31, 0
	v_mov_b32_e32 v47, 0
	v_mov_b32_e32 v192, 0
	v_mov_b32_e32 v193, 0
	s_waitcnt lgkmcnt(0)
	s_barrier
	v_max_f32_e32 v196, v64, v65
	v_max3_f32 v196, v196, v66, v67
	v_max3_f32 v196, v196, v68, v69
	v_max3_f32 v196, v196, v70, v71
	v_max3_f32 v196, v196, v72, v73
	v_max3_f32 v196, v196, v74, v75
	v_max3_f32 v196, v196, v76, v77
	v_max3_f32 v196, v196, v78, v79
	v_max3_f32 v196, v196, v80, v81
	v_max3_f32 v196, v196, v82, v83
	v_max3_f32 v196, v196, v84, v85
	v_max3_f32 v196, v196, v86, v87
	v_max3_f32 v196, v196, v88, v89
	v_max3_f32 v196, v196, v90, v91
	v_max3_f32 v196, v196, v92, v93
	v_max3_f32 v196, v196, v94, v95
	v_mov_b32_e32 v197, v196
	s_nop 1
	v_permlane32_swap_b32_e32 v196, v197
	v_max_f32_e32 v196, v196, v197
	s_mov_b32 s24, 0xefa18f08
	v_cmp_ngt_f32_e32 vcc, s24, v196
	s_nop 1
	v_cndmask_b32_e32 v198, 0, v196, vcc
	v_sub_f32_e32 v64, v64, v198
	v_sub_f32_e32 v65, v65, v198
	v_sub_f32_e32 v66, v66, v198
	v_sub_f32_e32 v67, v67, v198
	v_sub_f32_e32 v68, v68, v198
	v_sub_f32_e32 v69, v69, v198
	v_sub_f32_e32 v70, v70, v198
	v_sub_f32_e32 v71, v71, v198
	v_sub_f32_e32 v72, v72, v198
	v_sub_f32_e32 v73, v73, v198
	v_sub_f32_e32 v74, v74, v198
	v_sub_f32_e32 v75, v75, v198
	v_sub_f32_e32 v76, v76, v198
	v_sub_f32_e32 v77, v77, v198
	v_sub_f32_e32 v78, v78, v198
	v_sub_f32_e32 v79, v79, v198
	v_sub_f32_e32 v80, v80, v198
	v_sub_f32_e32 v81, v81, v198
	v_sub_f32_e32 v82, v82, v198
	v_sub_f32_e32 v83, v83, v198
	v_sub_f32_e32 v84, v84, v198
	v_sub_f32_e32 v85, v85, v198
	v_sub_f32_e32 v86, v86, v198
	v_sub_f32_e32 v87, v87, v198
	v_sub_f32_e32 v88, v88, v198
	v_sub_f32_e32 v89, v89, v198
	v_sub_f32_e32 v90, v90, v198
	v_sub_f32_e32 v91, v91, v198
	v_sub_f32_e32 v92, v92, v198
	v_sub_f32_e32 v93, v93, v198
	v_sub_f32_e32 v94, v94, v198
	v_sub_f32_e32 v95, v95, v198
	v_sub_f32_e32 v196, 0, v198
	v_bfe_u32 v197, v196, 16, 1
	v_add3_u32 v196, v196, v197, s45
	v_lshrrev_b32_e32 v197, 16, v196
	v_and_b32_e32 v196, 0xffff0000, v196
	v_sub_f32_e64 v196, -v198, v196
	v_bfe_u32 v199, v196, 16, 1
	v_add3_u32 v196, v196, v199, s45
	v_and_or_b32 v196, v196, s92, v197
	v_cndmask_b32_e64 v244, 0, v196, s[8:9]
	s_nop 1
	v_mfma_f32_32x32x16_bf16 v[48:63], v[240:243], v[244:247], 0
	s_mov_b32 s28, 0

; template <int MODE>
; DI void attn_item(const Params& p, int layer, int bh, int qb, char* lds) {
;     ...
;     b = bh / 4; hd = bh % 4;
;     const u16* Hb = (const u16*)(p.ws + OFF_H) + (size_t)b * S * DIN;
;     Qg = Hb + C_DQ + hd * 64; qstr = DIN; kstr = vstr = 64;
;     Kg = (const u16*)(p.ws + OFF_DK) + (size_t)(b * 4 + hd) * S * 64; Vg = (const u16*)(p.ws + OFF_DV) + (size_t)(b * 4 + hd) * S * 64;
;     ocol = 384 + hd * 64;
;   } else {
;     b = bh / 6; hd = bh % 6;
;     const u16* Hb = (const u16*)(p.ws + OFF_H) + (size_t)b * S * DIN;
;     Qg = Hb + C_SQ + hd * 64; qstr = DIN; kstr = vstr = 64;
;     Kg = (const u16*)(p.ws + OFF_SK) + (size_t)(b * 2 + hd / 3) * S * 64; Vg = (const u16*)(p.ws + OFF_SV) + (size_t)(b * 2 + hd / 3) * S * 64;
;     ocol = 640 + hd * 64;
;   }
;   float* brel = (float*)lds;
;   char* stage0 = lds + BREL_BYTES;
;   if (MODE != 0) {
;     const int bcol = MODE == 1 ? hd : 4 + hd;
;     for (int i = tid; i < 512; i += NTHR) {
;       int rel = i - 224, rc = rel < -128 ? -128 : (rel > 128 ? 128 : rel);
;       float bv = p.relb[t5_bucket(rc) * 10 + bcol] * LOG2E;
;       brel[i] = (MODE == 2 && rc != rel) ? -1e30f : bv;
;     }
;   }
;   bf16x8 qf[NMAP][QS];
;   {
;     const u16* qrow = Qg + (size_t)(q0w + l32) * qstr + hh * 8;
; #pragma unroll
;     for (int mp = 0; mp < NMAP; ++mp)
; #pragma unroll
;       for (int st = 0; st < QS; ++st) qf[mp][st] = *(const bf16x8*)(qrow + (mp * QS + st) * 16);
;   }
;   f32x16 O[NMAP][2]; float m = 0.f, l[NMAP];
; #pragma unroll
;   for (int mp = 0; mp < NMAP; ++mp) {
; #pragma unroll
;     for (int r = 0; r < 16; ++r) { O[mp][0][r] = 0.f; O[mp][1][r] = 0.f; }
;     l[mp] = 0.f;
;   }
;   if (MODE == 2) { m = p.sink[layer * 6 + hd] * LOG2E; l[0] = (hh == 0) ? 1.f : 0.f; }
;   int kt0 = 0, kt1 = S / 64;
;   if (MODE == 2) { kt0 = (q0 - 128) / 64; if (kt0 < 0) kt0 = 0; kt1 = (q0 + 384) / 64; if (kt1 > S / 64) kt1 = S / 64; }
;   const int nt = kt1 - kt0;
;   constexpr int KSTRG = MODE == 0 ? 96 : 64, VSTRG = 64;
;   u32x4 rkA[KCH], rvA[1], rkB[KCH], rvB[1];
;   const __amdgpu_buffer_rsrc_t krsrc = __builtin_amdgcn_make_buffer_rsrc((void*)Kg, 0, S * KSTRG * 2, 0x00027000);
;   const __amdgpu_buffer_rsrc_t vrsrc = __builtin_amdgcn_make_buffer_rsrc((void*)Vg, 0, S * VSTRG * 2, 0x00027000);
;     ...
;   __syncthreads();
;   gload(kt0, rkA, rvA); lstore(0, rkA, rvA);
.LBB0_449:
	s_or_b64 exec, exec, s[8:9]
	s_add_i32 s6, s60, 0xfffffd00
	s_lshr_b32 s6, s6, 5
	s_and_b32 s6, s6, 0x7fffff8
	s_or_b32 s8, s6, s55
	s_lshl_b32 s6, s8, 11
	s_and_b32 s52, s6, 0x6000
	s_mul_i32 s6, s52, 0x15c0
	s_add_u32 s6, s34, s6
	s_addc_u32 s7, s35, 0
	s_lshl_b32 s9, s20, 7
	s_add_u32 s6, s6, s9
	v_ashrrev_i32_e32 v0, 1, v6
	s_addc_u32 s7, s7, 0
	v_and_b32_e32 v7, 0xffffffe0, v0
	s_add_u32 s6, s6, 0x60583c0
	v_and_b32_e32 v203, 31, v6
	v_add_u32_e32 v168, s23, v7
	s_addc_u32 s7, s7, 0
	v_bfe_u32 v8, v6, 5, 1
	v_or_b32_e32 v2, v168, v203
	v_mov_b64_e32 v[0:1], s[6:7]
	v_mad_i64_i32 v[0:1], s[6:7], v2, s64, v[0:1]
	v_lshlrev_b32_e32 v4, 4, v8
	v_lshl_add_u64 v[10:11], v[0:1], 0, v[4:5]
	global_load_dwordx4 v[0:3], v[10:11], off
	global_load_dwordx4 v[120:123], v[10:11], off offset:32
	global_load_dwordx4 v[124:127], v[10:11], off offset:64
	global_load_dwordx4 v[128:131], v[10:11], off offset:96
	s_lshl_b32 s6, s8, 20
	v_readlane_b32 s8, v254, 41
	v_readlane_b32 s9, v254, 42
	s_add_u32 s8, s8, s6
	s_addc_u32 s7, s9, 0
	v_readlane_b32 s10, v254, 39
	v_readlane_b32 s11, v254, 40
	s_add_u32 s12, s10, s6
	s_addc_u32 s13, s11, 0
	s_and_b32 s9, s7, 0xffff
	v_lshlrev_b32_e32 v169, 4, v6
	s_waitcnt lgkmcnt(0)
	s_barrier
	s_and_b32 s13, s13, 0xffff
	s_mov_b32 s10, s14
	s_mov_b32 s11, s15
	s_and_b32 s49, s60, 3
	s_lshl_b32 s49, s49, 6
	v_and_b32_e32 v203, 31, v184
	v_bfe_u32 v197, v184, 5, 1
	v_lshlrev_b32_e32 v202, 2, v197
	v_mov_b32_e32 v198, 144
	v_mul_u32_u24_e32 v204, v203, v198
	v_lshl_add_u32 v204, v197, 4, v204
	v_bfe_u32 v198, v184, 2, 2
	v_lshl_add_u32 v198, v197, 2, v198
	v_mov_b32_e32 v199, 192
	v_mul_u32_u24_e32 v205, v198, v199
	v_bfe_u32 v198, v184, 4, 1
	v_lshl_add_u32 v205, v198, 5, v205
	v_and_b32_e32 v198, 3, v184
	v_lshl_add_u32 v205, v198, 3, v205
	v_lshrrev_b32_e32 v196, 3, v184
	v_and_b32_e32 v198, 7, v184
	v_mov_b32_e32 v199, 144
	v_mul_u32_u24_e32 v206, v196, v199
	v_lshl_add_u32 v206, v198, 4, v206
	v_mov_b32_e32 v199, 192
	v_mul_u32_u24_e32 v207, v196, v199
	v_lshl_add_u32 v207, v198, 4, v207
	v_lshlrev_b32_e32 v208, 4, v184
	v_cmp_eq_u32_e64 s[6:7], 0, v197
	v_sub_u32_e32 v196, v202, v203
	v_sub_u32_e32 v196, v196, v168
	v_add_u32_e32 v196, 0xe0, v196
	v_lshlrev_b32_e32 v209, 2, v196
	v_readfirstlane_b32 s4, v168
	s_nop 0
	s_add_i32 s24, s4, 0xffffff81
	s_ashr_i32 s24, s24, 6
	s_max_i32 s24, s24, 0
	s_add_i32 s25, s4, 0xde
	s_lshr_b32 s25, s25, 6
	buffer_load_dwordx4 v[132:135], v208, s[8:11], 0 offen
	buffer_load_dwordx4 v[136:139], v208, s[12:15], 0 offen
	s_movk_i32 s93, 0x2000
	buffer_load_dwordx4 v[140:143], v208, s[8:11], s93 offen
	v_mov_b32_e32 v144, 0
	v_mov_b32_e32 v145, 0
	v_mov_b32_e32 v146, 0
	v_mov_b32_e32 v147, 0
	ds_write_b128 v207, v[144:147] offset:54272
	ds_write_b128 v207, v[144:147] offset:60416
	s_waitcnt vmcnt(0)
	ds_write_b128 v206, v[132:135] offset:2048
	ds_write_b128 v207, v[136:139] offset:11264
	ds_write_b128 v206, v[140:143] offset:23552
	s_movk_i32 s93, 0x4000
	s_movk_i32 s28, 0x2000
	buffer_load_dwordx4 v[238:241], v208, s[8:11], s93 offen
	buffer_load_dwordx4 v[242:245], v208, s[12:15], s28 offen
	s_movk_i32 s93, 0x6000
	s_movk_i32 s28, 0x4000
	s_waitcnt lgkmcnt(0)
	s_barrier
	v_mov_b32_e32 v196, 0
	ds_read_b32 v210, v196 offset:384
	ds_read_b32 v211, v196 offset:1408
	ds_read_b128 v[222:225], v204 offset:2048
	ds_read_b128 v[226:229], v204 offset:2080
	ds_read_b128 v[230:233], v204 offset:6656
	ds_read_b128 v[234:237], v204 offset:6688
	s_waitcnt lgkmcnt(3)
	v_mfma_f32_32x32x16_bf16 v[88:103], v[222:225], v[0:3], 0
	s_waitcnt lgkmcnt(2)
	v_mfma_f32_32x32x16_bf16 v[88:103], v[226:229], v[120:123], v[88:103]
	s_waitcnt lgkmcnt(1)
	v_mfma_f32_32x32x16_bf16 v[104:119], v[230:233], v[0:3], 0
	s_waitcnt lgkmcnt(0)
	v_mfma_f32_32x32x16_bf16 v[104:119], v[234:237], v[120:123], v[104:119]
	v_mov_b32_e32 v56, 0
	v_mov_b32_e32 v57, 0
	v_mov_b32_e32 v58, 0
	v_mov_b32_e32 v59, 0
	v_mov_b32_e32 v60, 0
	v_mov_b32_e32 v61, 0
	v_mov_b32_e32 v62, 0
	v_mov_b32_e32 v63, 0
	v_mov_b32_e32 v64, 0
	v_mov_b32_e32 v65, 0
	v_mov_b32_e32 v66, 0
	v_mov_b32_e32 v67, 0
	v_mov_b32_e32 v68, 0
	v_mov_b32_e32 v69, 0
	v_mov_b32_e32 v70, 0
	v_mov_b32_e32 v71, 0
	v_mov_b32_e32 v24, 0
	v_mov_b32_e32 v25, 0
	v_mov_b32_e32 v26, 0
	v_mov_b32_e32 v27, 0
	v_mov_b32_e32 v28, 0
	v_mov_b32_e32 v29, 0
	v_mov_b32_e32 v30, 0
	v_mov_b32_e32 v31, 0
	v_mov_b32_e32 v32, 0
	v_mov_b32_e32 v33, 0
	v_mov_b32_e32 v34, 0
	v_mov_b32_e32 v35, 0
	v_mov_b32_e32 v36, 0
	v_mov_b32_e32 v37, 0
	v_mov_b32_e32 v38, 0
	v_mov_b32_e32 v39, 0
	v_mov_b32_e32 v40, 0
	v_mov_b32_e32 v41, 0
	v_mov_b32_e32 v42, 0
	v_mov_b32_e32 v43, 0
	v_mov_b32_e32 v44, 0
	v_mov_b32_e32 v45, 0
	v_mov_b32_e32 v46, 0
	v_mov_b32_e32 v47, 0
	v_mov_b32_e32 v48, 0
	v_mov_b32_e32 v49, 0
	v_mov_b32_e32 v50, 0
	v_mov_b32_e32 v51, 0
	v_mov_b32_e32 v52, 0
	v_mov_b32_e32 v53, 0
	v_mov_b32_e32 v54, 0
	v_mov_b32_e32 v55, 0
	v_mov_b32_e32 v8, 0
	v_mov_b32_e32 v9, 0
	v_mov_b32_e32 v10, 0
	v_mov_b32_e32 v11, 0
	v_mov_b32_e32 v12, 0
	v_mov_b32_e32 v13, 0
	v_mov_b32_e32 v14, 0
	v_mov_b32_e32 v15, 0
	v_mov_b32_e32 v16, 0
	v_mov_b32_e32 v17, 0
	v_mov_b32_e32 v18, 0
	v_mov_b32_e32 v19, 0
	v_mov_b32_e32 v20, 0
	v_mov_b32_e32 v21, 0
	v_mov_b32_e32 v22, 0
	v_mov_b32_e32 v23, 0
	v_mov_b32_e32 v164, 0
	v_mov_b32_e32 v165, 0
	v_mov_b32_e32 v166, 0
	v_mov_b32_e32 v167, 0
	v_mov_b32_e32 v172, 0
	v_mov_b32_e32 v173, 0
	v_mov_b32_e32 v174, 0
	v_mov_b32_e32 v175, 0
	v_mov_b32_e32 v176, 0
	v_mov_b32_e32 v177, 0
	v_mov_b32_e32 v178, 0
	v_mov_b32_e32 v179, 0
	v_mov_b32_e32 v180, 0
	v_mov_b32_e32 v181, 0
	v_mov_b32_e32 v182, 0
	v_mov_b32_e32 v183, 0
	v_mov_b32_e32 v170, 0
	v_mov_b32_e32 v171, 0
	v_mov_b32_e32 v201, 0
	v_mov_b32_e32 v200, 0
	s_waitcnt lgkmcnt(0)
	s_cmp_eq_u32 s24, 0
	s_cbranch_scc1 .Ldf_p_near
	v_add_f32_e32 v88, v88, v210
	v_add_f32_e32 v89, v89, v210
	v_add_f32_e32 v90, v90, v210
	v_add_f32_e32 v91, v91, v210
	v_add_f32_e32 v92, v92, v210
	v_add_f32_e32 v93, v93, v210
	v_add_f32_e32 v94, v94, v210
	v_add_f32_e32 v95, v95, v210
	v_add_f32_e32 v96, v96, v210
	v_add_f32_e32 v97, v97, v210
	v_add_f32_e32 v98, v98, v210
	v_add_f32_e32 v99, v99, v210
	v_add_f32_e32 v100, v100, v210
	v_add_f32_e32 v101, v101, v210
	v_add_f32_e32 v102, v102, v210
	v_add_f32_e32 v103, v103, v210
	v_add_f32_e32 v104, v104, v210
	v_add_f32_e32 v105, v105, v210
	v_add_f32_e32 v106, v106, v210
	v_add_f32_e32 v107, v107, v210
	v_add_f32_e32 v108, v108, v210
	v_add_f32_e32 v109, v109, v210
	v_add_f32_e32 v110, v110, v210
	v_add_f32_e32 v111, v111, v210
	v_add_f32_e32 v112, v112, v210
	v_add_f32_e32 v113, v113, v210
	v_add_f32_e32 v114, v114, v210
	v_add_f32_e32 v115, v115, v210
	v_add_f32_e32 v116, v116, v210
	v_add_f32_e32 v117, v117, v210
	v_add_f32_e32 v118, v118, v210
	v_add_f32_e32 v119, v119, v210
	s_branch .Ldf_p_biased
